# P5->P6 seam (same-XCC mode): wait for own + neighbour quad; only the two cross-XCD edge rows published by atomic swaps
# speedup vs baseline: 1.0096x; 1.0096x over previous
;     __device__ __forceinline__ void run(f32x4 (&acc)[2][2][4][2], const pg8::Unit& u, int wr, int wc, int fr_, int fq_, int buf) const {
;     ...
;         if (wr == 0 && fr == 0) {
; #pragma unroll
;             for (int bj = 0; bj < 2; ++bj)
; #pragma unroll
;                 for (int n = 0; n < 2; ++n) { float* ep = edge + ((size_t)gpm * 4 + 0) * FF2 + colg + 128 * bj + 4 * n; *(f32x4*)ep = acc[0][bj][0][n]; *(f32x4*)(ep + FF2) = acc[0][bj][1][n]; }
;         }
;         if (wr == 1 && fr == 15) {
; #pragma unroll
;             for (int bj = 0; bj < 2; ++bj)
; #pragma unroll
;                 for (int n = 0; n < 2; ++n) { float* ep = edge + ((size_t)gpm * 4 + 2) * FF2 + colg + 128 * bj + 4 * n; *(f32x4*)ep = acc[1][bj][2][n]; *(f32x4*)(ep + FF2) = acc[1][bj][3][n]; }
;         }
.LBB0_541:
	s_or_b64 exec, exec, s[2:3]
	v_fmamk_f32 v82, v151, 0x3a800000, v233
	v_mul_f32_e32 v83, 0x4b800000, v82
	v_cmp_gt_f32_e32 vcc, s81, v82
	s_waitcnt lgkmcnt(0)
	s_barrier
	s_add_i32 s5, s54, s70
	v_cndmask_b32_e32 v82, v82, v83, vcc
	v_rsq_f32_e32 v83, v82
	v_lshl_add_u32 v82, s52, 8, v146
	s_mul_hi_i32 s4, s5, 0x16000
	s_mul_i32 s5, s5, 0x16000
	v_mul_f32_e32 v84, 0x45800000, v83
	v_cndmask_b32_e32 v84, v83, v84, vcc
	v_pk_fma_f32 v[98:99], v[70:71], v[84:85], v[134:135] op_sel_hi:[1,0,1]
	v_or_b32_e32 v70, s14, v236
	v_pk_fma_f32 v[104:105], v[80:81], v[84:85], v[144:145] op_sel_hi:[1,0,1]
	v_pk_fma_f32 v[102:103], v[78:79], v[84:85], v[142:143] op_sel_hi:[1,0,1]
	v_pk_fma_f32 v[76:77], v[76:77], v[84:85], v[140:141] op_sel_hi:[1,0,1]
	v_pk_fma_f32 v[74:75], v[74:75], v[84:85], v[138:139] op_sel_hi:[1,0,1]
	v_pk_fma_f32 v[100:101], v[72:73], v[84:85], v[136:137] op_sel_hi:[1,0,1]
	v_pk_fma_f32 v[68:69], v[68:69], v[84:85], v[132:133] op_sel_hi:[1,0,1]
	v_pk_fma_f32 v[66:67], v[66:67], v[84:85], v[130:131] op_sel_hi:[1,0,1]
	v_cmp_eq_u32_e32 vcc, 0, v70
	v_ashrrev_i32_e32 v83, 31, v82
	s_and_saveexec_b64 s[2:3], vcc
	s_cbranch_execz .LBB0_543
	s_add_u32 s6, s22, s5
	s_addc_u32 s7, s23, s4
	v_lshl_add_u64 v[70:71], v[82:83], 2, s[6:7]
	v_add_co_u32_e32 v72, vcc, 0x5000, v70
	s_nop 1
	v_addc_co_u32_e32 v73, vcc, 0, v71, vcc
	s_cmp_eq_u32 s54, 16
	s_cbranch_scc1 .Ledge_at0
	global_store_dwordx4 v[70:71], v[118:121], off
	global_store_dwordx4 v[72:73], v[102:105], off offset:2048
	global_store_dwordx4 v[70:71], v[94:97], off offset:16
	global_store_dwordx4 v[72:73], v[74:77], off offset:2064
	global_store_dwordx4 v[70:71], v[106:109], off offset:512
	global_store_dwordx4 v[72:73], v[98:101], off offset:2560
	global_store_dwordx4 v[70:71], v[86:89], off offset:528
	global_store_dwordx4 v[72:73], v[66:69], off offset:2576
	s_branch .LBB0_543
.Ledge_at0:
	global_atomic_swap_x2 v[70:71], v[118:119], off
	global_atomic_swap_x2 v[70:71], v[120:121], off offset:8
	global_atomic_swap_x2 v[72:73], v[102:103], off offset:2048
	global_atomic_swap_x2 v[72:73], v[104:105], off offset:2056
	global_atomic_swap_x2 v[70:71], v[94:95], off offset:16
	global_atomic_swap_x2 v[70:71], v[96:97], off offset:24
	global_atomic_swap_x2 v[72:73], v[74:75], off offset:2064
	global_atomic_swap_x2 v[72:73], v[76:77], off offset:2072
	global_atomic_swap_x2 v[70:71], v[106:107], off offset:512
	global_atomic_swap_x2 v[70:71], v[108:109], off offset:520
	global_atomic_swap_x2 v[72:73], v[98:99], off offset:2560
	global_atomic_swap_x2 v[72:73], v[100:101], off offset:2568
	global_atomic_swap_x2 v[70:71], v[86:87], off offset:528
	global_atomic_swap_x2 v[70:71], v[88:89], off offset:536
	global_atomic_swap_x2 v[72:73], v[66:67], off offset:2576
	global_atomic_swap_x2 v[72:73], v[68:69], off offset:2584
.LBB0_543:
	s_or_b64 exec, exec, s[2:3]
	v_fmamk_f32 v70, v148, 0x3a800000, v233
	v_mul_f32_e32 v71, 0x4b800000, v70
	v_cmp_gt_f32_e32 vcc, s81, v70
	s_and_b64 s[2:3], s[26:27], s[0:1]
	s_nop 0
	v_cndmask_b32_e32 v70, v70, v71, vcc
	v_rsq_f32_e32 v70, v70
	s_nop 0
	v_mul_f32_e32 v71, 0x45800000, v70
	v_cndmask_b32_e32 v70, v70, v71, vcc
	v_pk_fma_f32 v[48:49], v[48:49], v[70:71], v[144:145] op_sel_hi:[1,0,1]
	v_pk_fma_f32 v[46:47], v[46:47], v[70:71], v[142:143] op_sel_hi:[1,0,1]
	v_pk_fma_f32 v[64:65], v[64:65], v[70:71], v[140:141] op_sel_hi:[1,0,1]
	v_pk_fma_f32 v[62:63], v[62:63], v[70:71], v[138:139] op_sel_hi:[1,0,1]
	v_pk_fma_f32 v[32:33], v[32:33], v[70:71], v[136:137] op_sel_hi:[1,0,1]
	v_pk_fma_f32 v[30:31], v[30:31], v[70:71], v[134:135] op_sel_hi:[1,0,1]
	v_pk_fma_f32 v[52:53], v[52:53], v[70:71], v[132:133] op_sel_hi:[1,0,1]
	v_pk_fma_f32 v[50:51], v[50:51], v[70:71], v[130:131] op_sel_hi:[1,0,1]
	s_and_saveexec_b64 s[0:1], s[2:3]
	s_cbranch_execz .LBB0_545
	s_add_u32 s2, s22, s5
	s_addc_u32 s3, s23, s4
	v_lshl_add_u64 v[70:71], v[82:83], 2, s[2:3]
	v_add_co_u32_e32 v72, vcc, 0xb000, v70
	s_nop 1
	v_addc_co_u32_e32 v73, vcc, 0, v71, vcc
	v_add_co_u32_e32 v70, vcc, 0x10000, v70
	s_nop 1
	v_addc_co_u32_e32 v71, vcc, 0, v71, vcc
	s_cmp_eq_u32 s54, 15
	s_cbranch_scc1 .Ledge_at1
	global_store_dwordx4 v[72:73], v[46:49], off
	global_store_dwordx4 v[70:71], v[2:5], off offset:2048
	global_store_dwordx4 v[72:73], v[62:65], off offset:16
	global_store_dwordx4 v[70:71], v[18:21], off offset:2064
	global_store_dwordx4 v[72:73], v[30:33], off offset:512
	global_store_dwordx4 v[70:71], v[6:9], off offset:2560
	global_store_dwordx4 v[72:73], v[50:53], off offset:528
	global_store_dwordx4 v[70:71], v[22:25], off offset:2576
	s_branch .LBB0_545
.Ledge_at1:
	global_atomic_swap_x2 v[72:73], v[46:47], off
	global_atomic_swap_x2 v[72:73], v[48:49], off offset:8
	global_atomic_swap_x2 v[70:71], v[2:3], off offset:2048
	global_atomic_swap_x2 v[70:71], v[4:5], off offset:2056
	global_atomic_swap_x2 v[72:73], v[62:63], off offset:16
	global_atomic_swap_x2 v[72:73], v[64:65], off offset:24
	global_atomic_swap_x2 v[70:71], v[18:19], off offset:2064
	global_atomic_swap_x2 v[70:71], v[20:21], off offset:2072
	global_atomic_swap_x2 v[72:73], v[30:31], off offset:512
	global_atomic_swap_x2 v[72:73], v[32:33], off offset:520
	global_atomic_swap_x2 v[70:71], v[6:7], off offset:2560
	global_atomic_swap_x2 v[70:71], v[8:9], off offset:2568
	global_atomic_swap_x2 v[72:73], v[50:51], off offset:528
	global_atomic_swap_x2 v[72:73], v[52:53], off offset:536
	global_atomic_swap_x2 v[70:71], v[22:23], off offset:2576
	global_atomic_swap_x2 v[70:71], v[24:25], off offset:2584
